# latent attention VALU trims: V^T operand quads read directly (4 ds_read_b64, no v_mov), shorter row-max tree
# baseline (speedup 1.0000x reference)
.LBB0_892:
	v_lshl_or_b32 v172, s12, 14, v159
	v_add_u32_e32 v2, v172, v158
	ds_read_b128 v[2:5], v2 offset:4096
	ds_read_b128 v[144:147], v157 offset:49152
	s_waitcnt lgkmcnt(0)
	s_nop 0
	v_mfma_f32_32x32x16_f16 v[128:143], v[2:5], v[144:147], v[194:209]
	v_add_u32_e32 v2, v172, v160
	ds_read_b128 v[2:5], v2 offset:4096
	ds_read_b128 v[10:13], v157 offset:57344
	s_waitcnt lgkmcnt(0)
	v_mfma_f32_32x32x16_f16 v[128:143], v[2:5], v[10:13], v[128:143]
	v_max3_f32 v2, v80, v81, v82
	v_max3_f32 v2, v2, v83, v84
	v_max3_f32 v2, v2, v85, v86
	v_max3_f32 v2, v2, v87, v88
	v_max3_f32 v2, v2, v89, v90
	v_max3_f32 v2, v2, v91, v92
	v_max3_f32 v2, v2, v93, v94
	v_max_f32_e32 v2, v2, v95
	v_cmp_lt_f32_e32 vcc, s61, v2
	s_cbranch_vccz .LBB0_894
	ds_bpermute_b32 v3, v153, v2
	s_waitcnt lgkmcnt(0)
	v_max_f32_e32 v3, v3, v3
	v_max_f32_e32 v2, v2, v3
	v_max_f32_e32 v2, v2, v2
	v_max_f32_e32 v2, 0, v2
	v_exp_f32_e64 v4, -v2
	v_add_f32_e32 v169, v169, v2
	v_pk_add_f32 v[80:81], v[80:81], v[2:3] op_sel_hi:[1,0] neg_lo:[0,1] neg_hi:[0,1]
	v_pk_add_f32 v[82:83], v[82:83], v[2:3] op_sel_hi:[1,0] neg_lo:[0,1] neg_hi:[0,1]
	v_mul_f32_e32 v171, v171, v4
	v_pk_add_f32 v[84:85], v[84:85], v[2:3] op_sel_hi:[1,0] neg_lo:[0,1] neg_hi:[0,1]
	v_pk_add_f32 v[86:87], v[86:87], v[2:3] op_sel_hi:[1,0] neg_lo:[0,1] neg_hi:[0,1]
	v_pk_add_f32 v[88:89], v[88:89], v[2:3] op_sel_hi:[1,0] neg_lo:[0,1] neg_hi:[0,1]
	v_pk_add_f32 v[90:91], v[90:91], v[2:3] op_sel_hi:[1,0] neg_lo:[0,1] neg_hi:[0,1]
	v_pk_add_f32 v[92:93], v[92:93], v[2:3] op_sel_hi:[1,0] neg_lo:[0,1] neg_hi:[0,1]
	v_pk_add_f32 v[94:95], v[94:95], v[2:3] op_sel_hi:[1,0] neg_lo:[0,1] neg_hi:[0,1]
	v_sub_f32_e32 v143, v143, v2
	v_sub_f32_e32 v142, v142, v2
	v_sub_f32_e32 v141, v141, v2
	v_sub_f32_e32 v140, v140, v2
	v_sub_f32_e32 v139, v139, v2
	v_sub_f32_e32 v138, v138, v2
	v_sub_f32_e32 v137, v137, v2
	v_sub_f32_e32 v136, v136, v2
	v_sub_f32_e32 v135, v135, v2
	v_sub_f32_e32 v134, v134, v2
	v_sub_f32_e32 v133, v133, v2
	v_sub_f32_e32 v132, v132, v2
	v_sub_f32_e32 v131, v131, v2
	v_sub_f32_e32 v130, v130, v2
	v_sub_f32_e32 v129, v129, v2
	v_sub_f32_e32 v128, v128, v2
	v_pk_mul_f32 v[30:31], v[30:31], v[4:5] op_sel_hi:[1,0]
	v_pk_mul_f32 v[28:29], v[28:29], v[4:5] op_sel_hi:[1,0]
	v_pk_mul_f32 v[26:27], v[26:27], v[4:5] op_sel_hi:[1,0]
	v_pk_mul_f32 v[24:25], v[24:25], v[4:5] op_sel_hi:[1,0]
	v_pk_mul_f32 v[22:23], v[22:23], v[4:5] op_sel_hi:[1,0]
	v_pk_mul_f32 v[20:21], v[20:21], v[4:5] op_sel_hi:[1,0]
	v_pk_mul_f32 v[18:19], v[18:19], v[4:5] op_sel_hi:[1,0]
	v_pk_mul_f32 v[16:17], v[16:17], v[4:5] op_sel_hi:[1,0]
	v_pk_mul_f32 v[46:47], v[46:47], v[4:5] op_sel_hi:[1,0]
	v_pk_mul_f32 v[44:45], v[44:45], v[4:5] op_sel_hi:[1,0]
	v_pk_mul_f32 v[42:43], v[42:43], v[4:5] op_sel_hi:[1,0]
	v_pk_mul_f32 v[40:41], v[40:41], v[4:5] op_sel_hi:[1,0]
	v_pk_mul_f32 v[38:39], v[38:39], v[4:5] op_sel_hi:[1,0]
	v_pk_mul_f32 v[36:37], v[36:37], v[4:5] op_sel_hi:[1,0]
	v_pk_mul_f32 v[34:35], v[34:35], v[4:5] op_sel_hi:[1,0]
	v_pk_mul_f32 v[32:33], v[32:33], v[4:5] op_sel_hi:[1,0]
	v_sub_f32_e32 v194, v194, v2
	v_sub_f32_e32 v195, v195, v2
	v_sub_f32_e32 v196, v196, v2
	v_sub_f32_e32 v197, v197, v2
	v_sub_f32_e32 v198, v198, v2
	v_sub_f32_e32 v199, v199, v2
	v_sub_f32_e32 v200, v200, v2
	v_sub_f32_e32 v201, v201, v2
	v_sub_f32_e32 v202, v202, v2
	v_sub_f32_e32 v203, v203, v2
	v_sub_f32_e32 v204, v204, v2
	v_sub_f32_e32 v205, v205, v2
	v_sub_f32_e32 v206, v206, v2
	v_sub_f32_e32 v207, v207, v2
	v_sub_f32_e32 v208, v208, v2
	v_sub_f32_e32 v209, v209, v2
	s_nop 1
.LBB0_894:
	v_exp_f32_e32 v173, v80
	v_add_u32_e32 v80, v172, v161
	ds_read_b64 v[246:247], v80 offset:8192
	v_add_u32_e32 v224, v172, v162
	v_exp_f32_e32 v177, v84
	v_exp_f32_e32 v178, v85
	v_exp_f32_e32 v179, v86
	v_exp_f32_e32 v180, v87
	ds_read_b64 v[248:249], v224 offset:8192
	ds_read_b64 v[86:87], v224 offset:12288
	ds_read_b64 v[84:85], v80 offset:12288
	v_exp_f32_e32 v174, v81
	v_exp_f32_e32 v175, v82
	v_exp_f32_e32 v176, v83
	v_exp_f32_e32 v185, v92
	v_exp_f32_e32 v186, v93
	v_exp_f32_e32 v187, v94
	v_exp_f32_e32 v188, v95
	s_waitcnt lgkmcnt(0)
	v_add_u32_e32 v80, v172, v163
	ds_read_b64 v[250:251], v80 offset:8192
	v_add_u32_e32 v224, v172, v164
	ds_read_b64 v[252:253], v224 offset:8192
	ds_read_b64 v[82:83], v224 offset:12288
	ds_read_b64 v[80:81], v80 offset:12288
	v_cvt_pkrtz_f16_f32 v2, v173, v174
	v_cvt_pkrtz_f16_f32 v3, v175, v176
	v_cvt_pkrtz_f16_f32 v4, v177, v178
	v_cvt_pkrtz_f16_f32 v5, v179, v180
	v_exp_f32_e32 v181, v88
	v_exp_f32_e32 v182, v89
	v_mfma_f32_32x32x16_f16 v[16:31], v[246:249], v[2:5], v[16:31]
	v_exp_f32_e32 v183, v90
	v_exp_f32_e32 v184, v91
	s_waitcnt lgkmcnt(0)
	v_mfma_f32_32x32x16_f16 v[32:47], v[84:87], v[2:5], v[32:47]
	v_cvt_pkrtz_f16_f32 v6, v181, v182
	v_cvt_pkrtz_f16_f32 v7, v183, v184
	v_cvt_pkrtz_f16_f32 v8, v185, v186
	v_cvt_pkrtz_f16_f32 v9, v187, v188
	v_add_u32_e32 v2, v172, v156
	s_nop 0
	v_mfma_f32_32x32x16_f16 v[16:31], v[250:253], v[6:9], v[16:31]
	v_mfma_f32_32x32x16_f16 v[32:47], v[80:83], v[6:9], v[32:47]
	ds_read_b128 v[2:5], v2 offset:4096
	ds_read_b128 v[6:9], v154 offset:16384
	s_waitcnt lgkmcnt(0)
	v_mfma_f32_32x32x16_f16 v[112:127], v[2:5], v[6:9], v[230:245]
	v_add_u32_e32 v2, v172, v155
	ds_read_b128 v[190:193], v2 offset:4096
	ds_read_b128 v[2:5], v154 offset:24576
	s_waitcnt lgkmcnt(0)
	v_mfma_f32_32x32x16_f16 v[112:127], v[190:193], v[2:5], v[112:127]
	v_max3_f32 v189, v96, v97, v98
	v_max3_f32 v189, v189, v99, v100
	v_max3_f32 v189, v189, v101, v102
	v_max3_f32 v189, v189, v103, v104
	v_max3_f32 v189, v189, v105, v106
	v_max3_f32 v189, v189, v107, v108
	v_max3_f32 v189, v189, v109, v110
	v_max_f32_e32 v189, v189, v111
	v_cmp_lt_f32_e32 vcc, s61, v189
	s_cbranch_vccz .LBB0_896
	ds_bpermute_b32 v190, v153, v189
	s_waitcnt lgkmcnt(0)
	v_max_f32_e32 v190, v190, v190
	v_max_f32_e32 v189, v189, v190
	v_max_f32_e32 v189, v189, v189
	v_max_f32_e32 v190, 0, v189
	v_exp_f32_e64 v192, -v190
	v_add_f32_e32 v168, v168, v190
	v_pk_add_f32 v[96:97], v[96:97], v[190:191] op_sel_hi:[1,0] neg_lo:[0,1] neg_hi:[0,1]
	v_pk_add_f32 v[98:99], v[98:99], v[190:191] op_sel_hi:[1,0] neg_lo:[0,1] neg_hi:[0,1]
	v_mul_f32_e32 v170, v170, v192
	v_pk_add_f32 v[100:101], v[100:101], v[190:191] op_sel_hi:[1,0] neg_lo:[0,1] neg_hi:[0,1]
	v_pk_add_f32 v[102:103], v[102:103], v[190:191] op_sel_hi:[1,0] neg_lo:[0,1] neg_hi:[0,1]
	v_pk_add_f32 v[104:105], v[104:105], v[190:191] op_sel_hi:[1,0] neg_lo:[0,1] neg_hi:[0,1]
	v_pk_add_f32 v[106:107], v[106:107], v[190:191] op_sel_hi:[1,0] neg_lo:[0,1] neg_hi:[0,1]
	v_pk_add_f32 v[108:109], v[108:109], v[190:191] op_sel_hi:[1,0] neg_lo:[0,1] neg_hi:[0,1]
	v_pk_add_f32 v[110:111], v[110:111], v[190:191] op_sel_hi:[1,0] neg_lo:[0,1] neg_hi:[0,1]
	v_sub_f32_e32 v127, v127, v190
	v_sub_f32_e32 v126, v126, v190
	v_sub_f32_e32 v125, v125, v190
	v_sub_f32_e32 v124, v124, v190
	v_sub_f32_e32 v123, v123, v190
	v_sub_f32_e32 v122, v122, v190
	v_sub_f32_e32 v121, v121, v190
	v_sub_f32_e32 v120, v120, v190
	v_sub_f32_e32 v119, v119, v190
	v_sub_f32_e32 v118, v118, v190
	v_sub_f32_e32 v117, v117, v190
	v_sub_f32_e32 v116, v116, v190
	v_sub_f32_e32 v115, v115, v190
	v_sub_f32_e32 v114, v114, v190
	v_sub_f32_e32 v113, v113, v190
	v_sub_f32_e32 v112, v112, v190
	v_pk_mul_f32 v[62:63], v[62:63], v[192:193] op_sel_hi:[1,0]
	v_pk_mul_f32 v[60:61], v[60:61], v[192:193] op_sel_hi:[1,0]
	v_pk_mul_f32 v[58:59], v[58:59], v[192:193] op_sel_hi:[1,0]
	v_pk_mul_f32 v[56:57], v[56:57], v[192:193] op_sel_hi:[1,0]
	v_pk_mul_f32 v[54:55], v[54:55], v[192:193] op_sel_hi:[1,0]
	v_pk_mul_f32 v[52:53], v[52:53], v[192:193] op_sel_hi:[1,0]
	v_pk_mul_f32 v[50:51], v[50:51], v[192:193] op_sel_hi:[1,0]
	v_pk_mul_f32 v[48:49], v[48:49], v[192:193] op_sel_hi:[1,0]
	v_pk_mul_f32 v[78:79], v[78:79], v[192:193] op_sel_hi:[1,0]
	v_pk_mul_f32 v[76:77], v[76:77], v[192:193] op_sel_hi:[1,0]
	v_pk_mul_f32 v[74:75], v[74:75], v[192:193] op_sel_hi:[1,0]
	v_pk_mul_f32 v[72:73], v[72:73], v[192:193] op_sel_hi:[1,0]
	v_pk_mul_f32 v[70:71], v[70:71], v[192:193] op_sel_hi:[1,0]
	v_pk_mul_f32 v[68:69], v[68:69], v[192:193] op_sel_hi:[1,0]
	v_pk_mul_f32 v[66:67], v[66:67], v[192:193] op_sel_hi:[1,0]
	v_pk_mul_f32 v[64:65], v[64:65], v[192:193] op_sel_hi:[1,0]
	v_sub_f32_e32 v230, v230, v190
	v_sub_f32_e32 v231, v231, v190
	v_sub_f32_e32 v232, v232, v190
	v_sub_f32_e32 v233, v233, v190
	v_sub_f32_e32 v234, v234, v190
	v_sub_f32_e32 v235, v235, v190
	v_sub_f32_e32 v236, v236, v190
	v_sub_f32_e32 v237, v237, v190
	v_sub_f32_e32 v238, v238, v190
	v_sub_f32_e32 v239, v239, v190
	v_sub_f32_e32 v240, v240, v190
	v_sub_f32_e32 v241, v241, v190
	v_sub_f32_e32 v242, v242, v190
	v_sub_f32_e32 v243, v243, v190
	v_sub_f32_e32 v244, v244, v190
	v_sub_f32_e32 v245, v245, v190
	s_nop 1
.LBB0_896:
	v_add_f32_e32 v173, 0, v173
	v_add_f32_e32 v173, v174, v173
	v_add_f32_e32 v173, v175, v173
	v_add_f32_e32 v173, v176, v173
	v_add_f32_e32 v173, v177, v173
	v_add_f32_e32 v173, v178, v173
	v_add_f32_e32 v173, v179, v173
	v_add_f32_e32 v173, v180, v173
	v_add_f32_e32 v173, v181, v173
	v_add_f32_e32 v173, v182, v173
	v_add_f32_e32 v173, v183, v173
	v_add_f32_e32 v173, v184, v173
	v_add_f32_e32 v173, v185, v173
	v_exp_f32_e32 v96, v96
	v_exp_f32_e32 v97, v97
	v_exp_f32_e32 v98, v98
	v_exp_f32_e32 v99, v99
	v_exp_f32_e32 v100, v100
	v_exp_f32_e32 v101, v101
	v_exp_f32_e32 v102, v102
	v_exp_f32_e32 v103, v103
	v_add_f32_e32 v173, v186, v173
	v_add_f32_e32 v173, v187, v173
	v_add_f32_e32 v173, v188, v173
	v_add_f32_e32 v171, v171, v173
	v_add_u32_e32 v173, s11, v159
	v_cvt_pkrtz_f16_f32 v174, v96, v97
	v_cvt_pkrtz_f16_f32 v175, v98, v99
	v_cvt_pkrtz_f16_f32 v176, v100, v101
	v_cvt_pkrtz_f16_f32 v177, v102, v103
	v_exp_f32_e32 v104, v104
	v_exp_f32_e32 v105, v105
	v_mfma_f32_32x32x16_f16 v[48:63], v[246:249], v[174:177], v[48:63]
	v_exp_f32_e32 v106, v106
	v_exp_f32_e32 v107, v107
	v_exp_f32_e32 v108, v108
	v_exp_f32_e32 v109, v109
	v_exp_f32_e32 v110, v110
	v_exp_f32_e32 v111, v111
	v_cvt_pkrtz_f16_f32 v178, v104, v105
	v_mfma_f32_32x32x16_f16 v[64:79], v[84:87], v[174:177], v[64:79]
	v_add_u32_e32 v174, v173, v158
	ds_read_b128 v[174:177], v174
	v_cvt_pkrtz_f16_f32 v179, v106, v107
	v_cvt_pkrtz_f16_f32 v180, v108, v109
	v_cvt_pkrtz_f16_f32 v181, v110, v111
	s_nop 1
	v_mfma_f32_32x32x16_f16 v[64:79], v[80:83], v[178:181], v[64:79]
	v_mfma_f32_32x32x16_f16 v[48:63], v[250:253], v[178:181], v[48:63]
	v_add_u32_e32 v178, v173, v160
	s_waitcnt lgkmcnt(0)
	s_nop 0
	v_mfma_f32_32x32x16_f16 v[80:95], v[174:177], v[144:147], v[194:209]
	ds_read_b128 v[144:147], v178
	s_waitcnt lgkmcnt(0)
	v_mfma_f32_32x32x16_f16 v[80:95], v[144:147], v[10:13], v[80:95]
	v_max3_f32 v10, v128, v129, v130
	v_max3_f32 v10, v10, v131, v132
	v_max3_f32 v10, v10, v133, v134
	v_max3_f32 v10, v10, v135, v136
	v_max3_f32 v10, v10, v137, v138
	v_max3_f32 v10, v10, v139, v140
	v_max3_f32 v10, v10, v141, v142
	v_max_f32_e32 v10, v10, v143
	v_cmp_lt_f32_e32 vcc, s61, v10
	s_cbranch_vccz .LBB0_898
	ds_bpermute_b32 v11, v153, v10
	s_waitcnt lgkmcnt(0)
	v_max_f32_e32 v11, v11, v11
	v_max_f32_e32 v10, v10, v11
	v_max_f32_e32 v10, v10, v10
	v_max_f32_e32 v10, 0, v10
	v_exp_f32_e64 v12, -v10
	v_add_f32_e32 v169, v169, v10
	v_pk_add_f32 v[128:129], v[128:129], v[10:11] op_sel_hi:[1,0] neg_lo:[0,1] neg_hi:[0,1]
	v_pk_add_f32 v[130:131], v[130:131], v[10:11] op_sel_hi:[1,0] neg_lo:[0,1] neg_hi:[0,1]
	v_mul_f32_e32 v171, v171, v12
	v_pk_add_f32 v[132:133], v[132:133], v[10:11] op_sel_hi:[1,0] neg_lo:[0,1] neg_hi:[0,1]
	v_pk_add_f32 v[134:135], v[134:135], v[10:11] op_sel_hi:[1,0] neg_lo:[0,1] neg_hi:[0,1]
	v_pk_add_f32 v[136:137], v[136:137], v[10:11] op_sel_hi:[1,0] neg_lo:[0,1] neg_hi:[0,1]
	v_pk_add_f32 v[138:139], v[138:139], v[10:11] op_sel_hi:[1,0] neg_lo:[0,1] neg_hi:[0,1]
	v_pk_add_f32 v[140:141], v[140:141], v[10:11] op_sel_hi:[1,0] neg_lo:[0,1] neg_hi:[0,1]
	v_pk_add_f32 v[142:143], v[142:143], v[10:11] op_sel_hi:[1,0] neg_lo:[0,1] neg_hi:[0,1]
	v_sub_f32_e32 v95, v95, v10
	v_sub_f32_e32 v94, v94, v10
	v_sub_f32_e32 v93, v93, v10
	v_sub_f32_e32 v92, v92, v10
	v_sub_f32_e32 v91, v91, v10
	v_sub_f32_e32 v90, v90, v10
	v_sub_f32_e32 v89, v89, v10
	v_sub_f32_e32 v88, v88, v10
	v_sub_f32_e32 v87, v87, v10
	v_sub_f32_e32 v86, v86, v10
	v_sub_f32_e32 v85, v85, v10
	v_sub_f32_e32 v84, v84, v10
	v_sub_f32_e32 v83, v83, v10
	v_sub_f32_e32 v82, v82, v10
	v_sub_f32_e32 v81, v81, v10
	v_sub_f32_e32 v80, v80, v10
	v_pk_mul_f32 v[30:31], v[30:31], v[12:13] op_sel_hi:[1,0]
	v_pk_mul_f32 v[28:29], v[28:29], v[12:13] op_sel_hi:[1,0]
	v_pk_mul_f32 v[26:27], v[26:27], v[12:13] op_sel_hi:[1,0]
	v_pk_mul_f32 v[24:25], v[24:25], v[12:13] op_sel_hi:[1,0]
	v_pk_mul_f32 v[22:23], v[22:23], v[12:13] op_sel_hi:[1,0]
	v_pk_mul_f32 v[20:21], v[20:21], v[12:13] op_sel_hi:[1,0]
	v_pk_mul_f32 v[18:19], v[18:19], v[12:13] op_sel_hi:[1,0]
	v_pk_mul_f32 v[16:17], v[16:17], v[12:13] op_sel_hi:[1,0]
	v_pk_mul_f32 v[46:47], v[46:47], v[12:13] op_sel_hi:[1,0]
	v_pk_mul_f32 v[44:45], v[44:45], v[12:13] op_sel_hi:[1,0]
	v_pk_mul_f32 v[42:43], v[42:43], v[12:13] op_sel_hi:[1,0]
	v_pk_mul_f32 v[40:41], v[40:41], v[12:13] op_sel_hi:[1,0]
	v_pk_mul_f32 v[38:39], v[38:39], v[12:13] op_sel_hi:[1,0]
	v_pk_mul_f32 v[36:37], v[36:37], v[12:13] op_sel_hi:[1,0]
	v_pk_mul_f32 v[34:35], v[34:35], v[12:13] op_sel_hi:[1,0]
	v_pk_mul_f32 v[32:33], v[32:33], v[12:13] op_sel_hi:[1,0]
	v_sub_f32_e32 v194, v194, v10
	v_sub_f32_e32 v195, v195, v10
	v_sub_f32_e32 v196, v196, v10
	v_sub_f32_e32 v197, v197, v10
	v_sub_f32_e32 v198, v198, v10
	v_sub_f32_e32 v199, v199, v10
	v_sub_f32_e32 v200, v200, v10
	v_sub_f32_e32 v201, v201, v10
	v_sub_f32_e32 v202, v202, v10
	v_sub_f32_e32 v203, v203, v10
	v_sub_f32_e32 v204, v204, v10
	v_sub_f32_e32 v205, v205, v10
	v_sub_f32_e32 v206, v206, v10
	v_sub_f32_e32 v207, v207, v10
	v_sub_f32_e32 v208, v208, v10
	v_sub_f32_e32 v209, v209, v10
	s_nop 1
.LBB0_898:
	v_add_f32_e32 v10, 0, v96
	v_add_f32_e32 v10, v97, v10
	v_add_f32_e32 v10, v98, v10
	v_add_f32_e32 v10, v99, v10
	v_add_f32_e32 v10, v100, v10
	v_add_f32_e32 v10, v101, v10
	v_add_f32_e32 v10, v102, v10
	v_add_f32_e32 v10, v103, v10
	v_add_f32_e32 v10, v104, v10
	v_add_f32_e32 v10, v105, v10
	v_add_f32_e32 v10, v106, v10
	v_add_f32_e32 v10, v107, v10
	v_add_f32_e32 v10, v108, v10
	v_add_f32_e32 v10, v109, v10
	v_add_f32_e32 v10, v110, v10
	v_add_f32_e32 v10, v111, v10
	v_add_f32_e32 v144, v170, v10
	v_add_u32_e32 v10, v172, v166
	ds_read_b64 v[246:247], v10 offset:8192
	v_add_u32_e32 v224, v172, v167
	v_exp_f32_e32 v145, v128
	v_exp_f32_e32 v146, v129
	v_exp_f32_e32 v147, v130
	v_exp_f32_e32 v170, v131
	ds_read_b64 v[248:249], v224 offset:8192
	ds_read_b64 v[130:131], v224 offset:12288
	ds_read_b64 v[128:129], v10 offset:12288
	v_exp_f32_e32 v174, v132
	v_exp_f32_e32 v175, v133
	v_exp_f32_e32 v176, v134
	v_exp_f32_e32 v177, v135
	v_exp_f32_e32 v178, v136
	v_exp_f32_e32 v179, v137
	v_exp_f32_e32 v180, v138
	v_exp_f32_e32 v181, v139
	s_waitcnt lgkmcnt(0)
	v_add_u32_e32 v10, v172, v1
	ds_read_b64 v[250:251], v10 offset:8192
	v_add_u32_e32 v224, v172, v165
	ds_read_b64 v[252:253], v224 offset:8192
	ds_read_b64 v[12:13], v224 offset:12288
	ds_read_b64 v[10:11], v10 offset:12288
	v_cvt_pkrtz_f16_f32 v96, v145, v146
	v_cvt_pkrtz_f16_f32 v97, v147, v170
	v_cvt_pkrtz_f16_f32 v98, v174, v175
	v_cvt_pkrtz_f16_f32 v99, v176, v177
	v_add_u32_e32 v172, v173, v155
	v_add_u32_e32 v173, v173, v156
	v_mfma_f32_32x32x16_f16 v[16:31], v[246:249], v[96:99], v[16:31]
	ds_read_b128 v[182:185], v173
	v_exp_f32_e32 v140, v140
	v_exp_f32_e32 v141, v141
	v_exp_f32_e32 v142, v142
	v_exp_f32_e32 v143, v143
	s_waitcnt lgkmcnt(0)
	v_mfma_f32_32x32x16_f16 v[32:47], v[128:131], v[96:99], v[32:47]
	v_cvt_pkrtz_f16_f32 v100, v178, v179
	v_cvt_pkrtz_f16_f32 v101, v180, v181
	v_cvt_pkrtz_f16_f32 v102, v140, v141
	v_cvt_pkrtz_f16_f32 v103, v142, v143
	s_nop 1
	v_mfma_f32_32x32x16_f16 v[16:31], v[250:253], v[100:103], v[16:31]
	s_nop 0
	v_mfma_f32_32x32x16_f16 v[32:47], v[10:13], v[100:103], v[32:47]
	s_nop 1
	v_mfma_f32_32x32x16_f16 v[96:111], v[182:185], v[6:9], v[230:245]
	ds_read_b128 v[6:9], v172
	s_waitcnt lgkmcnt(0)
	v_mfma_f32_32x32x16_f16 v[96:111], v[6:9], v[2:5], v[96:111]
	v_max3_f32 v2, v112, v113, v114
	v_max3_f32 v2, v2, v115, v116
	v_max3_f32 v2, v2, v117, v118
	v_max3_f32 v2, v2, v119, v120
	v_max3_f32 v2, v2, v121, v122
	v_max3_f32 v2, v2, v123, v124
	v_max3_f32 v2, v2, v125, v126
	v_max_f32_e32 v2, v2, v127
	v_cmp_lt_f32_e32 vcc, s61, v2
	s_cbranch_vccz .LBB0_900
	ds_bpermute_b32 v3, v153, v2
	s_waitcnt lgkmcnt(0)
	v_max_f32_e32 v3, v3, v3
	v_max_f32_e32 v2, v2, v3
	v_max_f32_e32 v2, v2, v2
	v_max_f32_e32 v2, 0, v2
	v_exp_f32_e64 v4, -v2
	v_add_f32_e32 v168, v168, v2
	v_pk_add_f32 v[112:113], v[112:113], v[2:3] op_sel_hi:[1,0] neg_lo:[0,1] neg_hi:[0,1]
	v_pk_add_f32 v[114:115], v[114:115], v[2:3] op_sel_hi:[1,0] neg_lo:[0,1] neg_hi:[0,1]
	v_mul_f32_e32 v144, v144, v4
	v_pk_add_f32 v[116:117], v[116:117], v[2:3] op_sel_hi:[1,0] neg_lo:[0,1] neg_hi:[0,1]
	v_pk_add_f32 v[118:119], v[118:119], v[2:3] op_sel_hi:[1,0] neg_lo:[0,1] neg_hi:[0,1]
	v_pk_add_f32 v[120:121], v[120:121], v[2:3] op_sel_hi:[1,0] neg_lo:[0,1] neg_hi:[0,1]
	v_pk_add_f32 v[122:123], v[122:123], v[2:3] op_sel_hi:[1,0] neg_lo:[0,1] neg_hi:[0,1]
	v_pk_add_f32 v[124:125], v[124:125], v[2:3] op_sel_hi:[1,0] neg_lo:[0,1] neg_hi:[0,1]
	v_pk_add_f32 v[126:127], v[126:127], v[2:3] op_sel_hi:[1,0] neg_lo:[0,1] neg_hi:[0,1]
	v_sub_f32_e32 v111, v111, v2
	v_sub_f32_e32 v110, v110, v2
	v_sub_f32_e32 v109, v109, v2
	v_sub_f32_e32 v108, v108, v2
	v_sub_f32_e32 v107, v107, v2
	v_sub_f32_e32 v106, v106, v2
	v_sub_f32_e32 v105, v105, v2
	v_sub_f32_e32 v104, v104, v2
	v_sub_f32_e32 v103, v103, v2
	v_sub_f32_e32 v102, v102, v2
	v_sub_f32_e32 v101, v101, v2
	v_sub_f32_e32 v100, v100, v2
	v_sub_f32_e32 v99, v99, v2
	v_sub_f32_e32 v98, v98, v2
	v_sub_f32_e32 v97, v97, v2
	v_sub_f32_e32 v96, v96, v2
	v_pk_mul_f32 v[62:63], v[62:63], v[4:5] op_sel_hi:[1,0]
	v_pk_mul_f32 v[60:61], v[60:61], v[4:5] op_sel_hi:[1,0]
	v_pk_mul_f32 v[58:59], v[58:59], v[4:5] op_sel_hi:[1,0]
	v_pk_mul_f32 v[56:57], v[56:57], v[4:5] op_sel_hi:[1,0]
	v_pk_mul_f32 v[54:55], v[54:55], v[4:5] op_sel_hi:[1,0]
	v_pk_mul_f32 v[52:53], v[52:53], v[4:5] op_sel_hi:[1,0]
	v_pk_mul_f32 v[50:51], v[50:51], v[4:5] op_sel_hi:[1,0]
	v_pk_mul_f32 v[48:49], v[48:49], v[4:5] op_sel_hi:[1,0]
	v_pk_mul_f32 v[78:79], v[78:79], v[4:5] op_sel_hi:[1,0]
	v_pk_mul_f32 v[76:77], v[76:77], v[4:5] op_sel_hi:[1,0]
	v_pk_mul_f32 v[74:75], v[74:75], v[4:5] op_sel_hi:[1,0]
	v_pk_mul_f32 v[72:73], v[72:73], v[4:5] op_sel_hi:[1,0]
	v_pk_mul_f32 v[70:71], v[70:71], v[4:5] op_sel_hi:[1,0]
	v_pk_mul_f32 v[68:69], v[68:69], v[4:5] op_sel_hi:[1,0]
	v_pk_mul_f32 v[66:67], v[66:67], v[4:5] op_sel_hi:[1,0]
	v_pk_mul_f32 v[64:65], v[64:65], v[4:5] op_sel_hi:[1,0]
	v_sub_f32_e32 v230, v230, v2
	v_sub_f32_e32 v231, v231, v2
	v_sub_f32_e32 v232, v232, v2
	v_sub_f32_e32 v233, v233, v2
	v_sub_f32_e32 v234, v234, v2
	v_sub_f32_e32 v235, v235, v2
	v_sub_f32_e32 v236, v236, v2
	v_sub_f32_e32 v237, v237, v2
	v_sub_f32_e32 v238, v238, v2
	v_sub_f32_e32 v239, v239, v2
	v_sub_f32_e32 v240, v240, v2
	v_sub_f32_e32 v241, v241, v2
	v_sub_f32_e32 v242, v242, v2
	v_sub_f32_e32 v243, v243, v2
	v_sub_f32_e32 v244, v244, v2
	v_sub_f32_e32 v245, v245, v2
	s_nop 1
.LBB0_900:
	v_add_f32_e32 v2, 0, v145
	v_add_f32_e32 v2, v146, v2
	v_add_f32_e32 v2, v147, v2
	v_add_f32_e32 v2, v170, v2
	v_add_f32_e32 v2, v174, v2
	v_add_f32_e32 v2, v175, v2
	v_add_f32_e32 v2, v176, v2
	v_add_f32_e32 v2, v177, v2
	v_add_f32_e32 v2, v178, v2
	v_add_f32_e32 v2, v179, v2
	v_add_f32_e32 v2, v180, v2
	v_add_f32_e32 v2, v181, v2
	v_add_f32_e32 v2, v140, v2
	v_add_f32_e32 v2, v141, v2
	v_add_f32_e32 v2, v142, v2
	v_add_f32_e32 v2, v143, v2
	v_add_f32_e32 v171, v171, v2
	v_exp_f32_e32 v2, v112
	v_exp_f32_e32 v4, v113
	v_exp_f32_e32 v5, v114
	v_exp_f32_e32 v6, v115
	v_add_f32_e32 v3, 0, v2
	v_exp_f32_e32 v7, v116
	v_add_f32_e32 v3, v4, v3
	v_exp_f32_e32 v8, v117
	v_add_f32_e32 v3, v5, v3
	v_exp_f32_e32 v9, v118
	v_add_f32_e32 v3, v6, v3
	v_exp_f32_e32 v112, v119
	v_add_f32_e32 v3, v7, v3
	v_exp_f32_e32 v113, v120
	v_add_f32_e32 v3, v8, v3
	v_exp_f32_e32 v114, v121
	v_add_f32_e32 v3, v9, v3
	v_exp_f32_e32 v115, v122
	v_add_f32_e32 v3, v112, v3
	v_exp_f32_e32 v116, v123
	v_add_f32_e32 v3, v113, v3
	v_exp_f32_e32 v117, v124
	v_add_f32_e32 v3, v114, v3
	v_exp_f32_e32 v118, v125
	v_add_f32_e32 v3, v115, v3
	v_exp_f32_e32 v119, v126
	v_add_f32_e32 v3, v116, v3
	v_exp_f32_e32 v120, v127
	v_add_f32_e32 v3, v117, v3
	v_add_f32_e32 v3, v118, v3
	v_add_f32_e32 v3, v119, v3
	v_add_f32_e32 v3, v120, v3
	v_add_f32_e32 v170, v144, v3
	v_cvt_pkrtz_f16_f32 v2, v2, v4
	v_cvt_pkrtz_f16_f32 v3, v5, v6
	v_cvt_pkrtz_f16_f32 v4, v7, v8
	v_cvt_pkrtz_f16_f32 v5, v9, v112
	v_cvt_pkrtz_f16_f32 v6, v113, v114
	v_cvt_pkrtz_f16_f32 v7, v115, v116
	v_mfma_f32_32x32x16_f16 v[48:63], v[246:249], v[2:5], v[48:63]
	v_cvt_pkrtz_f16_f32 v8, v117, v118
	v_cvt_pkrtz_f16_f32 v9, v119, v120
	s_waitcnt vmcnt(0)
	s_add_i32 s9, s9, 1
	v_lshl_add_u64 v[14:15], v[14:15], 0, s[42:43]
	v_lshl_add_u64 v[150:151], v[150:151], 0, s[66:67]
	s_cmp_lg_u32 s9, 35
	v_mfma_f32_32x32x16_f16 v[64:79], v[128:131], v[2:5], v[64:79]
	s_waitcnt vmcnt(0)
	s_barrier
	v_mfma_f32_32x32x16_f16 v[48:63], v[250:253], v[6:9], v[48:63]
	v_mfma_f32_32x32x16_f16 v[64:79], v[10:13], v[6:9], v[64:79]
	s_cbranch_scc0 .LBB0_902
	s_mov_b32 s12, s10
	s_branch .LBB0_888
